# P5 merge GEMM: mid-K gate hook and epilogue issue all 16 gate loads at once (was one load per vmcnt(0))
# speedup vs baseline: 1.0163x; 1.0163x over previous
.LBB0_547:
	s_cmpk_lg_i32 s10, 0x400
	s_cbranch_scc1 .LBB0_546
	v_add_u32_e32 v132, s29, v147
	v_lshl_add_u32 v2, v158, 3, s28
	v_ashrrev_i32_e32 v133, 31, v132
	v_ashrrev_i32_e32 v3, 31, v2
	v_lshlrev_b64 v[132:133], 12, v[132:133]
	v_lshlrev_b64 v[2:3], 1, v[2:3]
	v_lshl_add_u64 v[2:3], s[92:93], 0, v[2:3]
	v_lshl_add_u64 v[2:3], v[2:3], 0, v[132:133]
	s_mov_b64 s[12:13], 0x10000
	global_load_dwordx4 v[216:219], v[2:3], off
	global_load_dwordx4 v[220:223], v[2:3], off offset:256
	v_lshl_add_u64 v[2:3], v[2:3], 0, s[12:13]
	global_load_dwordx4 v[224:227], v[2:3], off
	global_load_dwordx4 v[228:231], v[2:3], off offset:256
	v_lshl_add_u64 v[2:3], v[2:3], 0, s[12:13]
	global_load_dwordx4 v[232:235], v[2:3], off
	global_load_dwordx4 v[236:239], v[2:3], off offset:256
	v_lshl_add_u64 v[2:3], v[2:3], 0, s[12:13]
	global_load_dwordx4 v[240:243], v[2:3], off
	global_load_dwordx4 v[244:247], v[2:3], off offset:256
	s_mov_b64 s[12:13], 0x50000
	v_lshl_add_u64 v[2:3], v[2:3], 0, s[12:13]
	s_mov_b64 s[12:13], 0x10000
	global_load_dwordx4 v[198:201], v[2:3], off
	global_load_dwordx4 v[202:205], v[2:3], off offset:256
	v_lshl_add_u64 v[2:3], v[2:3], 0, s[12:13]
	global_load_dwordx4 v[206:209], v[2:3], off
	global_load_dwordx4 v[210:213], v[2:3], off offset:256
	v_lshl_add_u64 v[2:3], v[2:3], 0, s[12:13]
	global_load_dwordx4 v[164:167], v[2:3], off
	global_load_dwordx4 v[168:171], v[2:3], off offset:256
	v_lshl_add_u64 v[2:3], v[2:3], 0, s[12:13]
	global_load_dwordx4 v[172:175], v[2:3], off
	global_load_dwordx4 v[132:135], v[2:3], off offset:256
	s_waitcnt vmcnt(15)
	v_lshlrev_b32_e32 v248, 16, v216
	v_and_b32_e32 v249, 0xffff0000, v216
	v_lshlrev_b32_e32 v250, 16, v217
	v_and_b32_e32 v251, 0xffff0000, v217
	v_lshlrev_b32_e32 v252, 16, v218
	v_and_b32_e32 v253, 0xffff0000, v218
	v_lshlrev_b32_e32 v176, 16, v219
	v_and_b32_e32 v177, 0xffff0000, v219
	v_pk_mul_f32 v[128:129], v[128:129], v[248:249]
	v_pk_mul_f32 v[130:131], v[130:131], v[250:251]
	v_pk_mul_f32 v[124:125], v[124:125], v[252:253]
	v_pk_mul_f32 v[126:127], v[126:127], v[176:177]
	s_waitcnt vmcnt(14)
	v_lshlrev_b32_e32 v248, 16, v220
	v_and_b32_e32 v249, 0xffff0000, v220
	v_lshlrev_b32_e32 v250, 16, v221
	v_and_b32_e32 v251, 0xffff0000, v221
	v_lshlrev_b32_e32 v252, 16, v222
	v_and_b32_e32 v253, 0xffff0000, v222
	v_lshlrev_b32_e32 v176, 16, v223
	v_and_b32_e32 v177, 0xffff0000, v223
	v_pk_mul_f32 v[120:121], v[120:121], v[248:249]
	v_pk_mul_f32 v[122:123], v[122:123], v[250:251]
	v_pk_mul_f32 v[116:117], v[116:117], v[252:253]
	v_pk_mul_f32 v[118:119], v[118:119], v[176:177]
	s_waitcnt vmcnt(13)
	v_lshlrev_b32_e32 v248, 16, v224
	v_and_b32_e32 v249, 0xffff0000, v224
	v_lshlrev_b32_e32 v250, 16, v225
	v_and_b32_e32 v251, 0xffff0000, v225
	v_lshlrev_b32_e32 v252, 16, v226
	v_and_b32_e32 v253, 0xffff0000, v226
	v_lshlrev_b32_e32 v176, 16, v227
	v_and_b32_e32 v177, 0xffff0000, v227
	v_pk_mul_f32 v[112:113], v[112:113], v[248:249]
	v_pk_mul_f32 v[114:115], v[114:115], v[250:251]
	v_pk_mul_f32 v[108:109], v[108:109], v[252:253]
	v_pk_mul_f32 v[110:111], v[110:111], v[176:177]
	s_waitcnt vmcnt(12)
	v_lshlrev_b32_e32 v248, 16, v228
	v_and_b32_e32 v249, 0xffff0000, v228
	v_lshlrev_b32_e32 v250, 16, v229
	v_and_b32_e32 v251, 0xffff0000, v229
	v_lshlrev_b32_e32 v252, 16, v230
	v_and_b32_e32 v253, 0xffff0000, v230
	v_lshlrev_b32_e32 v176, 16, v231
	v_and_b32_e32 v177, 0xffff0000, v231
	v_pk_mul_f32 v[104:105], v[104:105], v[248:249]
	v_pk_mul_f32 v[106:107], v[106:107], v[250:251]
	v_pk_mul_f32 v[100:101], v[100:101], v[252:253]
	v_pk_mul_f32 v[102:103], v[102:103], v[176:177]
	s_waitcnt vmcnt(11)
	v_lshlrev_b32_e32 v248, 16, v232
	v_and_b32_e32 v249, 0xffff0000, v232
	v_lshlrev_b32_e32 v250, 16, v233
	v_and_b32_e32 v251, 0xffff0000, v233
	v_lshlrev_b32_e32 v252, 16, v234
	v_and_b32_e32 v253, 0xffff0000, v234
	v_lshlrev_b32_e32 v176, 16, v235
	v_and_b32_e32 v177, 0xffff0000, v235
	v_pk_mul_f32 v[96:97], v[96:97], v[248:249]
	v_pk_mul_f32 v[98:99], v[98:99], v[250:251]
	v_pk_mul_f32 v[92:93], v[92:93], v[252:253]
	v_pk_mul_f32 v[94:95], v[94:95], v[176:177]
	s_waitcnt vmcnt(10)
	v_lshlrev_b32_e32 v248, 16, v236
	v_and_b32_e32 v249, 0xffff0000, v236
	v_lshlrev_b32_e32 v250, 16, v237
	v_and_b32_e32 v251, 0xffff0000, v237
	v_lshlrev_b32_e32 v252, 16, v238
	v_and_b32_e32 v253, 0xffff0000, v238
	v_lshlrev_b32_e32 v176, 16, v239
	v_and_b32_e32 v177, 0xffff0000, v239
	v_pk_mul_f32 v[88:89], v[88:89], v[248:249]
	v_pk_mul_f32 v[90:91], v[90:91], v[250:251]
	v_pk_mul_f32 v[84:85], v[84:85], v[252:253]
	v_pk_mul_f32 v[86:87], v[86:87], v[176:177]
	s_waitcnt vmcnt(9)
	v_lshlrev_b32_e32 v248, 16, v240
	v_and_b32_e32 v249, 0xffff0000, v240
	v_lshlrev_b32_e32 v250, 16, v241
	v_and_b32_e32 v251, 0xffff0000, v241
	v_lshlrev_b32_e32 v252, 16, v242
	v_and_b32_e32 v253, 0xffff0000, v242
	v_lshlrev_b32_e32 v176, 16, v243
	v_and_b32_e32 v177, 0xffff0000, v243
	v_pk_mul_f32 v[80:81], v[80:81], v[248:249]
	v_pk_mul_f32 v[82:83], v[82:83], v[250:251]
	v_pk_mul_f32 v[76:77], v[76:77], v[252:253]
	v_pk_mul_f32 v[78:79], v[78:79], v[176:177]
	s_waitcnt vmcnt(8)
	v_lshlrev_b32_e32 v248, 16, v244
	v_and_b32_e32 v249, 0xffff0000, v244
	v_lshlrev_b32_e32 v250, 16, v245
	v_and_b32_e32 v251, 0xffff0000, v245
	v_lshlrev_b32_e32 v252, 16, v246
	v_and_b32_e32 v253, 0xffff0000, v246
	v_lshlrev_b32_e32 v176, 16, v247
	v_and_b32_e32 v177, 0xffff0000, v247
	v_pk_mul_f32 v[72:73], v[72:73], v[248:249]
	v_pk_mul_f32 v[74:75], v[74:75], v[250:251]
	v_pk_mul_f32 v[68:69], v[68:69], v[252:253]
	v_pk_mul_f32 v[70:71], v[70:71], v[176:177]
	s_waitcnt vmcnt(7)
	v_lshlrev_b32_e32 v248, 16, v198
	v_and_b32_e32 v249, 0xffff0000, v198
	v_lshlrev_b32_e32 v250, 16, v199
	v_and_b32_e32 v251, 0xffff0000, v199
	v_lshlrev_b32_e32 v252, 16, v200
	v_and_b32_e32 v253, 0xffff0000, v200
	v_lshlrev_b32_e32 v176, 16, v201
	v_and_b32_e32 v177, 0xffff0000, v201
	v_pk_mul_f32 v[64:65], v[64:65], v[248:249]
	v_pk_mul_f32 v[66:67], v[66:67], v[250:251]
	v_pk_mul_f32 v[60:61], v[60:61], v[252:253]
	v_pk_mul_f32 v[62:63], v[62:63], v[176:177]
	s_waitcnt vmcnt(6)
	v_lshlrev_b32_e32 v248, 16, v202
	v_and_b32_e32 v249, 0xffff0000, v202
	v_lshlrev_b32_e32 v250, 16, v203
	v_and_b32_e32 v251, 0xffff0000, v203
	v_lshlrev_b32_e32 v252, 16, v204
	v_and_b32_e32 v253, 0xffff0000, v204
	v_lshlrev_b32_e32 v176, 16, v205
	v_and_b32_e32 v177, 0xffff0000, v205
	v_pk_mul_f32 v[56:57], v[56:57], v[248:249]
	v_pk_mul_f32 v[58:59], v[58:59], v[250:251]
	v_pk_mul_f32 v[52:53], v[52:53], v[252:253]
	v_pk_mul_f32 v[54:55], v[54:55], v[176:177]
	s_waitcnt vmcnt(5)
	v_lshlrev_b32_e32 v248, 16, v206
	v_and_b32_e32 v249, 0xffff0000, v206
	v_lshlrev_b32_e32 v250, 16, v207
	v_and_b32_e32 v251, 0xffff0000, v207
	v_lshlrev_b32_e32 v252, 16, v208
	v_and_b32_e32 v253, 0xffff0000, v208
	v_lshlrev_b32_e32 v176, 16, v209
	v_and_b32_e32 v177, 0xffff0000, v209
	v_pk_mul_f32 v[48:49], v[48:49], v[248:249]
	v_pk_mul_f32 v[50:51], v[50:51], v[250:251]
	v_pk_mul_f32 v[44:45], v[44:45], v[252:253]
	v_pk_mul_f32 v[46:47], v[46:47], v[176:177]
	s_waitcnt vmcnt(4)
	v_lshlrev_b32_e32 v248, 16, v210
	v_and_b32_e32 v249, 0xffff0000, v210
	v_lshlrev_b32_e32 v250, 16, v211
	v_and_b32_e32 v251, 0xffff0000, v211
	v_lshlrev_b32_e32 v252, 16, v212
	v_and_b32_e32 v253, 0xffff0000, v212
	v_lshlrev_b32_e32 v176, 16, v213
	v_and_b32_e32 v177, 0xffff0000, v213
	v_pk_mul_f32 v[40:41], v[40:41], v[248:249]
	v_pk_mul_f32 v[42:43], v[42:43], v[250:251]
	v_pk_mul_f32 v[36:37], v[36:37], v[252:253]
	v_pk_mul_f32 v[38:39], v[38:39], v[176:177]
	s_waitcnt vmcnt(3)
	v_lshlrev_b32_e32 v248, 16, v164
	v_and_b32_e32 v249, 0xffff0000, v164
	v_lshlrev_b32_e32 v250, 16, v165
	v_and_b32_e32 v251, 0xffff0000, v165
	v_lshlrev_b32_e32 v252, 16, v166
	v_and_b32_e32 v253, 0xffff0000, v166
	v_lshlrev_b32_e32 v176, 16, v167
	v_and_b32_e32 v177, 0xffff0000, v167
	v_pk_mul_f32 v[32:33], v[32:33], v[248:249]
	v_pk_mul_f32 v[34:35], v[34:35], v[250:251]
	v_pk_mul_f32 v[28:29], v[28:29], v[252:253]
	v_pk_mul_f32 v[30:31], v[30:31], v[176:177]
	s_waitcnt vmcnt(2)
	v_lshlrev_b32_e32 v248, 16, v168
	v_and_b32_e32 v249, 0xffff0000, v168
	v_lshlrev_b32_e32 v250, 16, v169
	v_and_b32_e32 v251, 0xffff0000, v169
	v_lshlrev_b32_e32 v252, 16, v170
	v_and_b32_e32 v253, 0xffff0000, v170
	v_lshlrev_b32_e32 v176, 16, v171
	v_and_b32_e32 v177, 0xffff0000, v171
	v_pk_mul_f32 v[24:25], v[24:25], v[248:249]
	v_pk_mul_f32 v[26:27], v[26:27], v[250:251]
	v_pk_mul_f32 v[20:21], v[20:21], v[252:253]
	v_pk_mul_f32 v[22:23], v[22:23], v[176:177]
	s_waitcnt vmcnt(1)
	v_lshlrev_b32_e32 v248, 16, v172
	v_and_b32_e32 v249, 0xffff0000, v172
	v_lshlrev_b32_e32 v250, 16, v173
	v_and_b32_e32 v251, 0xffff0000, v173
	v_lshlrev_b32_e32 v252, 16, v174
	v_and_b32_e32 v253, 0xffff0000, v174
	v_lshlrev_b32_e32 v176, 16, v175
	v_and_b32_e32 v177, 0xffff0000, v175
	v_pk_mul_f32 v[16:17], v[16:17], v[248:249]
	v_pk_mul_f32 v[18:19], v[18:19], v[250:251]
	v_pk_mul_f32 v[12:13], v[12:13], v[252:253]
	v_pk_mul_f32 v[14:15], v[14:15], v[176:177]
	s_waitcnt vmcnt(0)
	v_lshlrev_b32_e32 v248, 16, v132
	v_and_b32_e32 v249, 0xffff0000, v132
	v_lshlrev_b32_e32 v250, 16, v133
	v_and_b32_e32 v251, 0xffff0000, v133
	v_lshlrev_b32_e32 v252, 16, v134
	v_and_b32_e32 v253, 0xffff0000, v134
	v_lshlrev_b32_e32 v176, 16, v135
	v_and_b32_e32 v177, 0xffff0000, v135
	v_pk_mul_f32 v[8:9], v[8:9], v[248:249]
	v_pk_mul_f32 v[10:11], v[10:11], v[250:251]
	v_pk_mul_f32 v[4:5], v[4:5], v[252:253]
	v_pk_mul_f32 v[6:7], v[6:7], v[176:177]
	s_branch .LBB0_546

.LBB0_551:
	v_add_u32_e32 v154, s24, v159
	v_or_b32_e32 v2, s25, v162
	v_ashrrev_i32_e32 v155, 31, v154
	v_ashrrev_i32_e32 v3, 31, v2
	v_lshlrev_b64 v[2:3], 1, v[2:3]
	v_lshlrev_b64 v[156:157], 12, v[154:155]
	v_lshlrev_b64 v[154:155], 11, v[154:155]
	v_lshl_add_u64 v[156:157], s[92:93], 0, v[156:157]
	v_lshl_add_u64 v[154:155], s[42:43], 0, v[154:155]
	v_lshl_add_u64 v[156:157], v[156:157], 0, v[2:3]
	v_lshl_add_u64 v[154:155], v[154:155], 0, v[2:3]
	s_mov_b64 s[12:13], 0x10000
	global_load_dwordx4 v[216:219], v[156:157], off offset:2048
	global_load_dwordx4 v[220:223], v[156:157], off offset:2304
	v_lshl_add_u64 v[156:157], v[156:157], 0, s[12:13]
	global_load_dwordx4 v[224:227], v[156:157], off offset:2048
	global_load_dwordx4 v[228:231], v[156:157], off offset:2304
	v_lshl_add_u64 v[156:157], v[156:157], 0, s[12:13]
	global_load_dwordx4 v[232:235], v[156:157], off offset:2048
	global_load_dwordx4 v[236:239], v[156:157], off offset:2304
	v_lshl_add_u64 v[156:157], v[156:157], 0, s[12:13]
	global_load_dwordx4 v[240:243], v[156:157], off offset:2048
	global_load_dwordx4 v[244:247], v[156:157], off offset:2304
	s_mov_b64 s[12:13], 0x50000
	v_lshl_add_u64 v[156:157], v[156:157], 0, s[12:13]
	s_mov_b64 s[12:13], 0x10000
	global_load_dwordx4 v[198:201], v[156:157], off offset:2048
	global_load_dwordx4 v[202:205], v[156:157], off offset:2304
	v_lshl_add_u64 v[156:157], v[156:157], 0, s[12:13]
	global_load_dwordx4 v[206:209], v[156:157], off offset:2048
	global_load_dwordx4 v[210:213], v[156:157], off offset:2304
	v_lshl_add_u64 v[156:157], v[156:157], 0, s[12:13]
	global_load_dwordx4 v[164:167], v[156:157], off offset:2048
	global_load_dwordx4 v[168:171], v[156:157], off offset:2304
	v_lshl_add_u64 v[156:157], v[156:157], 0, s[12:13]
	global_load_dwordx4 v[172:175], v[156:157], off offset:2048
	global_load_dwordx4 v[132:135], v[156:157], off offset:2304
	s_mov_b64 s[12:13], 0x8000
	s_waitcnt vmcnt(15)
	v_lshlrev_b32_e32 v248, 16, v216
	v_and_b32_e32 v249, 0xffff0000, v216
	v_lshlrev_b32_e32 v250, 16, v217
	v_and_b32_e32 v251, 0xffff0000, v217
	v_lshlrev_b32_e32 v252, 16, v218
	v_and_b32_e32 v253, 0xffff0000, v218
	v_lshlrev_b32_e32 v176, 16, v219
	v_and_b32_e32 v177, 0xffff0000, v219
	v_max_f32_e32 v248, 0xda24260, v248
	v_max_f32_e32 v249, 0xda24260, v249
	v_max_f32_e32 v250, 0xda24260, v250
	v_max_f32_e32 v251, 0xda24260, v251
	v_max_f32_e32 v252, 0xda24260, v252
	v_max_f32_e32 v253, 0xda24260, v253
	v_max_f32_e32 v176, 0xda24260, v176
	v_max_f32_e32 v177, 0xda24260, v177
	v_pk_mul_f32 v[128:129], v[128:129], v[248:249]
	v_pk_mul_f32 v[130:131], v[130:131], v[250:251]
	v_pk_mul_f32 v[124:125], v[124:125], v[252:253]
	v_pk_mul_f32 v[126:127], v[126:127], v[176:177]
	v_cvt_pk_bf16_f32 v216, v128, v129
	v_cvt_pk_bf16_f32 v217, v130, v131
	v_cvt_pk_bf16_f32 v218, v124, v125
	v_cvt_pk_bf16_f32 v219, v126, v127
	global_store_dwordx4 v[154:155], v[216:219], off
	s_waitcnt vmcnt(15)
	v_lshlrev_b32_e32 v248, 16, v220
	v_and_b32_e32 v249, 0xffff0000, v220
	v_lshlrev_b32_e32 v250, 16, v221
	v_and_b32_e32 v251, 0xffff0000, v221
	v_lshlrev_b32_e32 v252, 16, v222
	v_and_b32_e32 v253, 0xffff0000, v222
	v_lshlrev_b32_e32 v176, 16, v223
	v_and_b32_e32 v177, 0xffff0000, v223
	v_max_f32_e32 v248, 0xda24260, v248
	v_max_f32_e32 v249, 0xda24260, v249
	v_max_f32_e32 v250, 0xda24260, v250
	v_max_f32_e32 v251, 0xda24260, v251
	v_max_f32_e32 v252, 0xda24260, v252
	v_max_f32_e32 v253, 0xda24260, v253
	v_max_f32_e32 v176, 0xda24260, v176
	v_max_f32_e32 v177, 0xda24260, v177
	v_pk_mul_f32 v[120:121], v[120:121], v[248:249]
	v_pk_mul_f32 v[122:123], v[122:123], v[250:251]
	v_pk_mul_f32 v[116:117], v[116:117], v[252:253]
	v_pk_mul_f32 v[118:119], v[118:119], v[176:177]
	v_cvt_pk_bf16_f32 v220, v120, v121
	v_cvt_pk_bf16_f32 v221, v122, v123
	v_cvt_pk_bf16_f32 v222, v116, v117
	v_cvt_pk_bf16_f32 v223, v118, v119
	global_store_dwordx4 v[154:155], v[220:223], off offset:256
	v_lshl_add_u64 v[154:155], v[154:155], 0, s[12:13]
	s_waitcnt vmcnt(15)
	v_lshlrev_b32_e32 v248, 16, v224
	v_and_b32_e32 v249, 0xffff0000, v224
	v_lshlrev_b32_e32 v250, 16, v225
	v_and_b32_e32 v251, 0xffff0000, v225
	v_lshlrev_b32_e32 v252, 16, v226
	v_and_b32_e32 v253, 0xffff0000, v226
	v_lshlrev_b32_e32 v176, 16, v227
	v_and_b32_e32 v177, 0xffff0000, v227
	v_max_f32_e32 v248, 0xda24260, v248
	v_max_f32_e32 v249, 0xda24260, v249
	v_max_f32_e32 v250, 0xda24260, v250
	v_max_f32_e32 v251, 0xda24260, v251
	v_max_f32_e32 v252, 0xda24260, v252
	v_max_f32_e32 v253, 0xda24260, v253
	v_max_f32_e32 v176, 0xda24260, v176
	v_max_f32_e32 v177, 0xda24260, v177
	v_pk_mul_f32 v[112:113], v[112:113], v[248:249]
	v_pk_mul_f32 v[114:115], v[114:115], v[250:251]
	v_pk_mul_f32 v[108:109], v[108:109], v[252:253]
	v_pk_mul_f32 v[110:111], v[110:111], v[176:177]
	v_cvt_pk_bf16_f32 v224, v112, v113
	v_cvt_pk_bf16_f32 v225, v114, v115
	v_cvt_pk_bf16_f32 v226, v108, v109
	v_cvt_pk_bf16_f32 v227, v110, v111
	global_store_dwordx4 v[154:155], v[224:227], off
	s_waitcnt vmcnt(15)
	v_lshlrev_b32_e32 v248, 16, v228
	v_and_b32_e32 v249, 0xffff0000, v228
	v_lshlrev_b32_e32 v250, 16, v229
	v_and_b32_e32 v251, 0xffff0000, v229
	v_lshlrev_b32_e32 v252, 16, v230
	v_and_b32_e32 v253, 0xffff0000, v230
	v_lshlrev_b32_e32 v176, 16, v231
	v_and_b32_e32 v177, 0xffff0000, v231
	v_max_f32_e32 v248, 0xda24260, v248
	v_max_f32_e32 v249, 0xda24260, v249
	v_max_f32_e32 v250, 0xda24260, v250
	v_max_f32_e32 v251, 0xda24260, v251
	v_max_f32_e32 v252, 0xda24260, v252
	v_max_f32_e32 v253, 0xda24260, v253
	v_max_f32_e32 v176, 0xda24260, v176
	v_max_f32_e32 v177, 0xda24260, v177
	v_pk_mul_f32 v[104:105], v[104:105], v[248:249]
	v_pk_mul_f32 v[106:107], v[106:107], v[250:251]
	v_pk_mul_f32 v[100:101], v[100:101], v[252:253]
	v_pk_mul_f32 v[102:103], v[102:103], v[176:177]
	v_cvt_pk_bf16_f32 v228, v104, v105
	v_cvt_pk_bf16_f32 v229, v106, v107
	v_cvt_pk_bf16_f32 v230, v100, v101
	v_cvt_pk_bf16_f32 v231, v102, v103
	global_store_dwordx4 v[154:155], v[228:231], off offset:256
	v_lshl_add_u64 v[154:155], v[154:155], 0, s[12:13]
	s_waitcnt vmcnt(15)
	v_lshlrev_b32_e32 v248, 16, v232
	v_and_b32_e32 v249, 0xffff0000, v232
	v_lshlrev_b32_e32 v250, 16, v233
	v_and_b32_e32 v251, 0xffff0000, v233
	v_lshlrev_b32_e32 v252, 16, v234
	v_and_b32_e32 v253, 0xffff0000, v234
	v_lshlrev_b32_e32 v176, 16, v235
	v_and_b32_e32 v177, 0xffff0000, v235
	v_max_f32_e32 v248, 0xda24260, v248
	v_max_f32_e32 v249, 0xda24260, v249
	v_max_f32_e32 v250, 0xda24260, v250
	v_max_f32_e32 v251, 0xda24260, v251
	v_max_f32_e32 v252, 0xda24260, v252
	v_max_f32_e32 v253, 0xda24260, v253
	v_max_f32_e32 v176, 0xda24260, v176
	v_max_f32_e32 v177, 0xda24260, v177
	v_pk_mul_f32 v[96:97], v[96:97], v[248:249]
	v_pk_mul_f32 v[98:99], v[98:99], v[250:251]
	v_pk_mul_f32 v[92:93], v[92:93], v[252:253]
	v_pk_mul_f32 v[94:95], v[94:95], v[176:177]
	v_cvt_pk_bf16_f32 v232, v96, v97
	v_cvt_pk_bf16_f32 v233, v98, v99
	v_cvt_pk_bf16_f32 v234, v92, v93
	v_cvt_pk_bf16_f32 v235, v94, v95
	global_store_dwordx4 v[154:155], v[232:235], off
	s_waitcnt vmcnt(15)
	v_lshlrev_b32_e32 v248, 16, v236
	v_and_b32_e32 v249, 0xffff0000, v236
	v_lshlrev_b32_e32 v250, 16, v237
	v_and_b32_e32 v251, 0xffff0000, v237
	v_lshlrev_b32_e32 v252, 16, v238
	v_and_b32_e32 v253, 0xffff0000, v238
	v_lshlrev_b32_e32 v176, 16, v239
	v_and_b32_e32 v177, 0xffff0000, v239
	v_max_f32_e32 v248, 0xda24260, v248
	v_max_f32_e32 v249, 0xda24260, v249
	v_max_f32_e32 v250, 0xda24260, v250
	v_max_f32_e32 v251, 0xda24260, v251
	v_max_f32_e32 v252, 0xda24260, v252
	v_max_f32_e32 v253, 0xda24260, v253
	v_max_f32_e32 v176, 0xda24260, v176
	v_max_f32_e32 v177, 0xda24260, v177
	v_pk_mul_f32 v[88:89], v[88:89], v[248:249]
	v_pk_mul_f32 v[90:91], v[90:91], v[250:251]
	v_pk_mul_f32 v[84:85], v[84:85], v[252:253]
	v_pk_mul_f32 v[86:87], v[86:87], v[176:177]
	v_cvt_pk_bf16_f32 v236, v88, v89
	v_cvt_pk_bf16_f32 v237, v90, v91
	v_cvt_pk_bf16_f32 v238, v84, v85
	v_cvt_pk_bf16_f32 v239, v86, v87
	global_store_dwordx4 v[154:155], v[236:239], off offset:256
	v_lshl_add_u64 v[154:155], v[154:155], 0, s[12:13]
	s_waitcnt vmcnt(15)
	v_lshlrev_b32_e32 v248, 16, v240
	v_and_b32_e32 v249, 0xffff0000, v240
	v_lshlrev_b32_e32 v250, 16, v241
	v_and_b32_e32 v251, 0xffff0000, v241
	v_lshlrev_b32_e32 v252, 16, v242
	v_and_b32_e32 v253, 0xffff0000, v242
	v_lshlrev_b32_e32 v176, 16, v243
	v_and_b32_e32 v177, 0xffff0000, v243
	v_max_f32_e32 v248, 0xda24260, v248
	v_max_f32_e32 v249, 0xda24260, v249
	v_max_f32_e32 v250, 0xda24260, v250
	v_max_f32_e32 v251, 0xda24260, v251
	v_max_f32_e32 v252, 0xda24260, v252
	v_max_f32_e32 v253, 0xda24260, v253
	v_max_f32_e32 v176, 0xda24260, v176
	v_max_f32_e32 v177, 0xda24260, v177
	v_pk_mul_f32 v[80:81], v[80:81], v[248:249]
	v_pk_mul_f32 v[82:83], v[82:83], v[250:251]
	v_pk_mul_f32 v[76:77], v[76:77], v[252:253]
	v_pk_mul_f32 v[78:79], v[78:79], v[176:177]
	v_cvt_pk_bf16_f32 v240, v80, v81
	v_cvt_pk_bf16_f32 v241, v82, v83
	v_cvt_pk_bf16_f32 v242, v76, v77
	v_cvt_pk_bf16_f32 v243, v78, v79
	global_store_dwordx4 v[154:155], v[240:243], off
	s_waitcnt vmcnt(15)
	v_lshlrev_b32_e32 v248, 16, v244
	v_and_b32_e32 v249, 0xffff0000, v244
	v_lshlrev_b32_e32 v250, 16, v245
	v_and_b32_e32 v251, 0xffff0000, v245
	v_lshlrev_b32_e32 v252, 16, v246
	v_and_b32_e32 v253, 0xffff0000, v246
	v_lshlrev_b32_e32 v176, 16, v247
	v_and_b32_e32 v177, 0xffff0000, v247
	v_max_f32_e32 v248, 0xda24260, v248
	v_max_f32_e32 v249, 0xda24260, v249
	v_max_f32_e32 v250, 0xda24260, v250
	v_max_f32_e32 v251, 0xda24260, v251
	v_max_f32_e32 v252, 0xda24260, v252
	v_max_f32_e32 v253, 0xda24260, v253
	v_max_f32_e32 v176, 0xda24260, v176
	v_max_f32_e32 v177, 0xda24260, v177
	v_pk_mul_f32 v[72:73], v[72:73], v[248:249]
	v_pk_mul_f32 v[74:75], v[74:75], v[250:251]
	v_pk_mul_f32 v[68:69], v[68:69], v[252:253]
	v_pk_mul_f32 v[70:71], v[70:71], v[176:177]
	v_cvt_pk_bf16_f32 v244, v72, v73
	v_cvt_pk_bf16_f32 v245, v74, v75
	v_cvt_pk_bf16_f32 v246, v68, v69
	v_cvt_pk_bf16_f32 v247, v70, v71
	global_store_dwordx4 v[154:155], v[244:247], off offset:256
	s_mov_b64 s[12:13], 0x28000
	v_lshl_add_u64 v[154:155], v[154:155], 0, s[12:13]
	s_mov_b64 s[12:13], 0x8000
	s_waitcnt vmcnt(15)
	v_lshlrev_b32_e32 v248, 16, v198
	v_and_b32_e32 v249, 0xffff0000, v198
	v_lshlrev_b32_e32 v250, 16, v199
	v_and_b32_e32 v251, 0xffff0000, v199
	v_lshlrev_b32_e32 v252, 16, v200
	v_and_b32_e32 v253, 0xffff0000, v200
	v_lshlrev_b32_e32 v176, 16, v201
	v_and_b32_e32 v177, 0xffff0000, v201
	v_max_f32_e32 v248, 0xda24260, v248
	v_max_f32_e32 v249, 0xda24260, v249
	v_max_f32_e32 v250, 0xda24260, v250
	v_max_f32_e32 v251, 0xda24260, v251
	v_max_f32_e32 v252, 0xda24260, v252
	v_max_f32_e32 v253, 0xda24260, v253
	v_max_f32_e32 v176, 0xda24260, v176
	v_max_f32_e32 v177, 0xda24260, v177
	v_pk_mul_f32 v[64:65], v[64:65], v[248:249]
	v_pk_mul_f32 v[66:67], v[66:67], v[250:251]
	v_pk_mul_f32 v[60:61], v[60:61], v[252:253]
	v_pk_mul_f32 v[62:63], v[62:63], v[176:177]
	v_cvt_pk_bf16_f32 v198, v64, v65
	v_cvt_pk_bf16_f32 v199, v66, v67
	v_cvt_pk_bf16_f32 v200, v60, v61
	v_cvt_pk_bf16_f32 v201, v62, v63
	global_store_dwordx4 v[154:155], v[198:201], off
	s_waitcnt vmcnt(15)
	v_lshlrev_b32_e32 v248, 16, v202
	v_and_b32_e32 v249, 0xffff0000, v202
	v_lshlrev_b32_e32 v250, 16, v203
	v_and_b32_e32 v251, 0xffff0000, v203
	v_lshlrev_b32_e32 v252, 16, v204
	v_and_b32_e32 v253, 0xffff0000, v204
	v_lshlrev_b32_e32 v176, 16, v205
	v_and_b32_e32 v177, 0xffff0000, v205
	v_max_f32_e32 v248, 0xda24260, v248
	v_max_f32_e32 v249, 0xda24260, v249
	v_max_f32_e32 v250, 0xda24260, v250
	v_max_f32_e32 v251, 0xda24260, v251
	v_max_f32_e32 v252, 0xda24260, v252
	v_max_f32_e32 v253, 0xda24260, v253
	v_max_f32_e32 v176, 0xda24260, v176
	v_max_f32_e32 v177, 0xda24260, v177
	v_pk_mul_f32 v[56:57], v[56:57], v[248:249]
	v_pk_mul_f32 v[58:59], v[58:59], v[250:251]
	v_pk_mul_f32 v[52:53], v[52:53], v[252:253]
	v_pk_mul_f32 v[54:55], v[54:55], v[176:177]
	v_cvt_pk_bf16_f32 v202, v56, v57
	v_cvt_pk_bf16_f32 v203, v58, v59
	v_cvt_pk_bf16_f32 v204, v52, v53
	v_cvt_pk_bf16_f32 v205, v54, v55
	global_store_dwordx4 v[154:155], v[202:205], off offset:256
	v_lshl_add_u64 v[154:155], v[154:155], 0, s[12:13]
	s_waitcnt vmcnt(15)
	v_lshlrev_b32_e32 v248, 16, v206
	v_and_b32_e32 v249, 0xffff0000, v206
	v_lshlrev_b32_e32 v250, 16, v207
	v_and_b32_e32 v251, 0xffff0000, v207
	v_lshlrev_b32_e32 v252, 16, v208
	v_and_b32_e32 v253, 0xffff0000, v208
	v_lshlrev_b32_e32 v176, 16, v209
	v_and_b32_e32 v177, 0xffff0000, v209
	v_max_f32_e32 v248, 0xda24260, v248
	v_max_f32_e32 v249, 0xda24260, v249
	v_max_f32_e32 v250, 0xda24260, v250
	v_max_f32_e32 v251, 0xda24260, v251
	v_max_f32_e32 v252, 0xda24260, v252
	v_max_f32_e32 v253, 0xda24260, v253
	v_max_f32_e32 v176, 0xda24260, v176
	v_max_f32_e32 v177, 0xda24260, v177
	v_pk_mul_f32 v[48:49], v[48:49], v[248:249]
	v_pk_mul_f32 v[50:51], v[50:51], v[250:251]
	v_pk_mul_f32 v[44:45], v[44:45], v[252:253]
	v_pk_mul_f32 v[46:47], v[46:47], v[176:177]
	v_cvt_pk_bf16_f32 v206, v48, v49
	v_cvt_pk_bf16_f32 v207, v50, v51
	v_cvt_pk_bf16_f32 v208, v44, v45
	v_cvt_pk_bf16_f32 v209, v46, v47
	global_store_dwordx4 v[154:155], v[206:209], off
	s_waitcnt vmcnt(15)
	v_lshlrev_b32_e32 v248, 16, v210
	v_and_b32_e32 v249, 0xffff0000, v210
	v_lshlrev_b32_e32 v250, 16, v211
	v_and_b32_e32 v251, 0xffff0000, v211
	v_lshlrev_b32_e32 v252, 16, v212
	v_and_b32_e32 v253, 0xffff0000, v212
	v_lshlrev_b32_e32 v176, 16, v213
	v_and_b32_e32 v177, 0xffff0000, v213
	v_max_f32_e32 v248, 0xda24260, v248
	v_max_f32_e32 v249, 0xda24260, v249
	v_max_f32_e32 v250, 0xda24260, v250
	v_max_f32_e32 v251, 0xda24260, v251
	v_max_f32_e32 v252, 0xda24260, v252
	v_max_f32_e32 v253, 0xda24260, v253
	v_max_f32_e32 v176, 0xda24260, v176
	v_max_f32_e32 v177, 0xda24260, v177
	v_pk_mul_f32 v[40:41], v[40:41], v[248:249]
	v_pk_mul_f32 v[42:43], v[42:43], v[250:251]
	v_pk_mul_f32 v[36:37], v[36:37], v[252:253]
	v_pk_mul_f32 v[38:39], v[38:39], v[176:177]
	v_cvt_pk_bf16_f32 v210, v40, v41
	v_cvt_pk_bf16_f32 v211, v42, v43
	v_cvt_pk_bf16_f32 v212, v36, v37
	v_cvt_pk_bf16_f32 v213, v38, v39
	global_store_dwordx4 v[154:155], v[210:213], off offset:256
	v_lshl_add_u64 v[154:155], v[154:155], 0, s[12:13]
	s_waitcnt vmcnt(15)
	v_lshlrev_b32_e32 v248, 16, v164
	v_and_b32_e32 v249, 0xffff0000, v164
	v_lshlrev_b32_e32 v250, 16, v165
	v_and_b32_e32 v251, 0xffff0000, v165
	v_lshlrev_b32_e32 v252, 16, v166
	v_and_b32_e32 v253, 0xffff0000, v166
	v_lshlrev_b32_e32 v176, 16, v167
	v_and_b32_e32 v177, 0xffff0000, v167
	v_max_f32_e32 v248, 0xda24260, v248
	v_max_f32_e32 v249, 0xda24260, v249
	v_max_f32_e32 v250, 0xda24260, v250
	v_max_f32_e32 v251, 0xda24260, v251
	v_max_f32_e32 v252, 0xda24260, v252
	v_max_f32_e32 v253, 0xda24260, v253
	v_max_f32_e32 v176, 0xda24260, v176
	v_max_f32_e32 v177, 0xda24260, v177
	v_pk_mul_f32 v[32:33], v[32:33], v[248:249]
	v_pk_mul_f32 v[34:35], v[34:35], v[250:251]
	v_pk_mul_f32 v[28:29], v[28:29], v[252:253]
	v_pk_mul_f32 v[30:31], v[30:31], v[176:177]
	v_cvt_pk_bf16_f32 v164, v32, v33
	v_cvt_pk_bf16_f32 v165, v34, v35
	v_cvt_pk_bf16_f32 v166, v28, v29
	v_cvt_pk_bf16_f32 v167, v30, v31
	global_store_dwordx4 v[154:155], v[164:167], off
	s_waitcnt vmcnt(15)
	v_lshlrev_b32_e32 v248, 16, v168
	v_and_b32_e32 v249, 0xffff0000, v168
	v_lshlrev_b32_e32 v250, 16, v169
	v_and_b32_e32 v251, 0xffff0000, v169
	v_lshlrev_b32_e32 v252, 16, v170
	v_and_b32_e32 v253, 0xffff0000, v170
	v_lshlrev_b32_e32 v176, 16, v171
	v_and_b32_e32 v177, 0xffff0000, v171
	v_max_f32_e32 v248, 0xda24260, v248
	v_max_f32_e32 v249, 0xda24260, v249
	v_max_f32_e32 v250, 0xda24260, v250
	v_max_f32_e32 v251, 0xda24260, v251
	v_max_f32_e32 v252, 0xda24260, v252
	v_max_f32_e32 v253, 0xda24260, v253
	v_max_f32_e32 v176, 0xda24260, v176
	v_max_f32_e32 v177, 0xda24260, v177
	v_pk_mul_f32 v[24:25], v[24:25], v[248:249]
	v_pk_mul_f32 v[26:27], v[26:27], v[250:251]
	v_pk_mul_f32 v[20:21], v[20:21], v[252:253]
	v_pk_mul_f32 v[22:23], v[22:23], v[176:177]
	v_cvt_pk_bf16_f32 v168, v24, v25
	v_cvt_pk_bf16_f32 v169, v26, v27
	v_cvt_pk_bf16_f32 v170, v20, v21
	v_cvt_pk_bf16_f32 v171, v22, v23
	global_store_dwordx4 v[154:155], v[168:171], off offset:256
	v_lshl_add_u64 v[154:155], v[154:155], 0, s[12:13]
	s_waitcnt vmcnt(15)
	v_lshlrev_b32_e32 v248, 16, v172
	v_and_b32_e32 v249, 0xffff0000, v172
	v_lshlrev_b32_e32 v250, 16, v173
	v_and_b32_e32 v251, 0xffff0000, v173
	v_lshlrev_b32_e32 v252, 16, v174
	v_and_b32_e32 v253, 0xffff0000, v174
	v_lshlrev_b32_e32 v176, 16, v175
	v_and_b32_e32 v177, 0xffff0000, v175
	v_max_f32_e32 v248, 0xda24260, v248
	v_max_f32_e32 v249, 0xda24260, v249
	v_max_f32_e32 v250, 0xda24260, v250
	v_max_f32_e32 v251, 0xda24260, v251
	v_max_f32_e32 v252, 0xda24260, v252
	v_max_f32_e32 v253, 0xda24260, v253
	v_max_f32_e32 v176, 0xda24260, v176
	v_max_f32_e32 v177, 0xda24260, v177
	v_pk_mul_f32 v[16:17], v[16:17], v[248:249]
	v_pk_mul_f32 v[18:19], v[18:19], v[250:251]
	v_pk_mul_f32 v[12:13], v[12:13], v[252:253]
	v_pk_mul_f32 v[14:15], v[14:15], v[176:177]
	v_cvt_pk_bf16_f32 v172, v16, v17
	v_cvt_pk_bf16_f32 v173, v18, v19
	v_cvt_pk_bf16_f32 v174, v12, v13
	v_cvt_pk_bf16_f32 v175, v14, v15
	global_store_dwordx4 v[154:155], v[172:175], off
	s_waitcnt vmcnt(15)
	v_lshlrev_b32_e32 v248, 16, v132
	v_and_b32_e32 v249, 0xffff0000, v132
	v_lshlrev_b32_e32 v250, 16, v133
	v_and_b32_e32 v251, 0xffff0000, v133
	v_lshlrev_b32_e32 v252, 16, v134
	v_and_b32_e32 v253, 0xffff0000, v134
	v_lshlrev_b32_e32 v176, 16, v135
	v_and_b32_e32 v177, 0xffff0000, v135
	v_max_f32_e32 v248, 0xda24260, v248
	v_max_f32_e32 v249, 0xda24260, v249
	v_max_f32_e32 v250, 0xda24260, v250
	v_max_f32_e32 v251, 0xda24260, v251
	v_max_f32_e32 v252, 0xda24260, v252
	v_max_f32_e32 v253, 0xda24260, v253
	v_max_f32_e32 v176, 0xda24260, v176
	v_max_f32_e32 v177, 0xda24260, v177
	v_pk_mul_f32 v[8:9], v[8:9], v[248:249]
	v_pk_mul_f32 v[10:11], v[10:11], v[250:251]
	v_pk_mul_f32 v[4:5], v[4:5], v[252:253]
	v_pk_mul_f32 v[6:7], v[6:7], v[176:177]
	v_cvt_pk_bf16_f32 v132, v8, v9
	v_cvt_pk_bf16_f32 v133, v10, v11
	v_cvt_pk_bf16_f32 v134, v4, v5
	v_cvt_pk_bf16_f32 v135, v6, v7
	global_store_dwordx4 v[154:155], v[132:135], off offset:256
	s_mov_b64 s[10:11], -1
	s_andn2_b64 vcc, exec, s[40:41]
	s_cbranch_vccnz .LBB0_538
	s_andn2_b64 vcc, exec, s[2:3]
	s_cbranch_vccnz .LBB0_537
	s_barrier
	s_branch .LBB0_537
